# waves 4-7 issue all 8 LDS-DMA pieces inside the six VALU-free QK gaps (none in gaps that carry exps)
# baseline (speedup 1.0000x reference)
; __device__ __forceinline__ void glds16x4(const void* k0, const void* k1, const void* v0, const void* v1, unsigned voff, unsigned lk0, unsigned lk1, unsigned lv0, unsigned lv1) { unsigned keep;
;     asm volatile("s_mov_b32 %0, m0\n\t"
;                  "s_mov_b32 m0, %6\n\ts_nop 0\n\tglobal_load_lds_dwordx4 %1, %2\n\t"
;                  "s_mov_b32 m0, %7\n\ts_nop 0\n\tglobal_load_lds_dwordx4 %1, %3\n\t"
;                  "s_mov_b32 m0, %8\n\ts_nop 0\n\tglobal_load_lds_dwordx4 %1, %4\n\t"
;                  "s_mov_b32 m0, %9\n\ts_nop 0\n\tglobal_load_lds_dwordx4 %1, %5\n\t"
;                  "s_mov_b32 m0, %0"
;                  : "=&s"(keep) : "v"(voff), "s"(k0), "s"(k1), "s"(v0), "s"(v1), "s"(lk0), "s"(lk1), "s"(lv0), "s"(lv1) : "memory"); }
; __device__ __forceinline__ void attn_unit(LAS unsigned char* L, bf16_t* QKV, size_t rowbase, int S, int h, int qb, float lam, const float* subln, unsigned* kmax) {
;     ...
;     for (int t = 0; t < NT; t += 4) { TILE(t, 0); TILE(t + 1, 1); TILE(t + 2, 2); TILE(t + 3, 3); }
.Lattn_G:
.LG_loop:
	s_add_i32 s69, s68, -3
	s_mov_b32 m0, s53
	v_mfma_f32_32x32x16_bf16 v[96:111], v[132:135], v[116:119], v[64:79]
	global_load_lds_dwordx4 v163, s[4:5]
	s_add_i32 m0, s53, 0xfffff000
	s_nop 0
	global_load_lds_dwordx4 v250, s[4:5]
	s_mov_b32 m0, s58
	v_mfma_f32_32x32x16_bf16 v[96:111], v[140:143], v[120:123], v[96:111]
	global_load_lds_dwordx4 v254, s[4:5]
	s_add_i32 m0, s58, 0xfffff000
	s_nop 0
	global_load_lds_dwordx4 v251, s[4:5]
	s_mov_b32 m0, s25
	s_waitcnt lgkmcnt(10)
	v_mfma_f32_32x32x16_bf16 v[96:111], v[148:151], v[124:127], v[96:111]
	global_load_lds_dwordx4 v255, s[4:5]
	ds_read_b64_tr_b16 v[132:133], v176 offset:4096
	ds_read_b64_tr_b16 v[134:135], v177 offset:6144
	s_mov_b32 m0, s63
	s_waitcnt lgkmcnt(10)
	v_mfma_f32_32x32x16_bf16 v[96:111], v[80:83], v[112:115], v[96:111]
	global_load_lds_dwordx4 v253, s[4:5]
	ds_read_b64_tr_b16 v[140:141], v183 offset:4096
	ds_read_b64_tr_b16 v[142:143], v184 offset:6144
	s_add_i32 m0, s25, 0xfffff000
	v_mfma_f32_32x32x16_bf16 v[80:95], v[128:131], v[112:115], v[64:79]
	global_load_lds_dwordx4 v252, s[4:5]
	ds_read_b64_tr_b16 v[128:129], v174 offset:4096
	ds_read_b64_tr_b16 v[130:131], v175 offset:6144
	s_add_i32 m0, s63, 0xfffff000
	v_mfma_f32_32x32x16_bf16 v[80:95], v[136:139], v[116:119], v[80:95]
	global_load_lds_dwordx4 v195, s[4:5]
	s_nop 1
	v_mfma_f32_32x32x16_bf16 v[80:95], v[144:147], v[120:123], v[80:95]
	v_exp_f32_e32 v96, v96
	v_exp_f32_e32 v97, v97
	v_exp_f32_e32 v98, v98
	v_mfma_f32_32x32x16_bf16 v[80:95], v[152:155], v[124:127], v[80:95]
	v_exp_f32_e32 v99, v99
	v_exp_f32_e32 v100, v100
	v_exp_f32_e32 v101, v101
	v_exp_f32_e32 v102, v102
	v_exp_f32_e32 v103, v103
	v_cvt_pk_bf16_f32 v208, v96, v97
	v_cvt_pk_bf16_f32 v209, v98, v99
	v_cvt_pk_bf16_f32 v210, v100, v101
	v_cvt_pk_bf16_f32 v211, v102, v103
	v_exp_f32_e32 v104, v104
	v_exp_f32_e32 v105, v105
	s_waitcnt lgkmcnt(6)
	v_mfma_f32_32x32x16_bf16 v[48:63], v[224:227], v[208:211], v[48:63]
	v_exp_f32_e32 v106, v106
	v_exp_f32_e32 v107, v107
	v_exp_f32_e32 v108, v108
	ds_read_b64_tr_b16 v[136:137], v178 offset:4096
	ds_read_b64_tr_b16 v[138:139], v179 offset:6144
	v_mfma_f32_32x32x16_bf16 v[32:47], v[228:231], v[208:211], v[32:47]
	v_exp_f32_e32 v109, v109
	v_exp_f32_e32 v110, v110
	v_exp_f32_e32 v111, v111
	ds_read_b64_tr_b16 v[144:145], v174 offset:8192
	ds_read_b64_tr_b16 v[146:147], v175 offset:10240
	v_mfma_f32_32x32x16_bf16 v[16:31], v[232:235], v[208:211], v[16:31]
	v_cvt_pk_bf16_f32 v212, v104, v105
	v_cvt_pk_bf16_f32 v213, v106, v107
	v_cvt_pk_bf16_f32 v214, v108, v109
	v_cvt_pk_bf16_f32 v215, v110, v111
	v_add_f32_e32 v187, v96, v187
	v_add_f32_e32 v192, v97, v192
	ds_read_b64_tr_b16 v[148:149], v176 offset:8192
	ds_read_b64_tr_b16 v[150:151], v177 offset:10240
	v_mfma_f32_32x32x16_bf16 v[0:15], v[236:239], v[208:211], v[0:15]
	v_add_f32_e32 v193, v98, v193
	v_add_f32_e32 v194, v99, v194
	v_add_f32_e32 v187, v100, v187
	v_add_f32_e32 v192, v101, v192
	v_add_f32_e32 v193, v102, v193
	v_add_f32_e32 v194, v103, v194
	ds_read_b64_tr_b16 v[152:153], v178 offset:8192
	ds_read_b64_tr_b16 v[154:155], v179 offset:10240
	s_waitcnt lgkmcnt(6)
	v_mfma_f32_32x32x16_bf16 v[48:63], v[128:131], v[212:215], v[48:63]
	v_exp_f32_e32 v80, v80
	v_exp_f32_e32 v81, v81
	v_exp_f32_e32 v82, v82
	ds_read_b64_tr_b16 v[240:241], v183 offset:8192
	ds_read_b64_tr_b16 v[242:243], v184 offset:10240
	ds_read_b128 v[128:131], v188 offset:24576
	v_mfma_f32_32x32x16_bf16 v[32:47], v[132:135], v[212:215], v[32:47]
	v_exp_f32_e32 v83, v83
	v_exp_f32_e32 v84, v84
	v_exp_f32_e32 v85, v85
	ds_read_b64_tr_b16 v[196:197], v174 offset:12288
	ds_read_b64_tr_b16 v[198:199], v175 offset:14336
	ds_read_b128 v[132:135], v189 offset:16384
	v_mfma_f32_32x32x16_bf16 v[16:31], v[136:139], v[212:215], v[16:31]
	v_exp_f32_e32 v86, v86
	v_exp_f32_e32 v87, v87
	v_cvt_pk_bf16_f32 v216, v80, v81
	v_cvt_pk_bf16_f32 v217, v82, v83
	ds_read_b64_tr_b16 v[200:201], v176 offset:12288
	ds_read_b64_tr_b16 v[202:203], v177 offset:14336
	ds_read_b128 v[136:139], v189 offset:24576
	v_mfma_f32_32x32x16_bf16 v[0:15], v[140:143], v[212:215], v[0:15]
	v_cvt_pk_bf16_f32 v218, v84, v85
	v_cvt_pk_bf16_f32 v219, v86, v87
	v_add_f32_e32 v187, v104, v187
	v_add_f32_e32 v192, v105, v192
	v_add_f32_e32 v193, v106, v193
	v_add_f32_e32 v194, v107, v194
	s_waitcnt lgkmcnt(12)
	ds_read_b64_tr_b16 v[204:205], v178 offset:12288
	ds_read_b64_tr_b16 v[206:207], v179 offset:14336
	ds_read_b128 v[140:143], v190 offset:16384
	s_waitcnt lgkmcnt(10)
	v_mfma_f32_32x32x16_bf16 v[48:63], v[144:147], v[216:219], v[48:63]
	v_exp_f32_e32 v88, v88
	v_exp_f32_e32 v89, v89
	v_exp_f32_e32 v90, v90
	ds_read_b64_tr_b16 v[246:247], v183 offset:12288
	ds_read_b64_tr_b16 v[248:249], v184 offset:14336
	ds_read_b128 v[144:147], v190 offset:24576
	v_mfma_f32_32x32x16_bf16 v[32:47], v[148:151], v[216:219], v[32:47]
	v_exp_f32_e32 v91, v91
	v_exp_f32_e32 v92, v92
	v_exp_f32_e32 v93, v93
	ds_read_b128 v[148:151], v191 offset:16384
	v_mfma_f32_32x32x16_bf16 v[16:31], v[152:155], v[216:219], v[16:31]
	v_exp_f32_e32 v94, v94
	v_exp_f32_e32 v95, v95
	v_cvt_pk_bf16_f32 v220, v88, v89
	v_cvt_pk_bf16_f32 v221, v90, v91
	ds_read_b128 v[152:155], v191 offset:24576
	v_mfma_f32_32x32x16_bf16 v[0:15], v[240:243], v[216:219], v[0:15]
	v_cvt_pk_bf16_f32 v222, v92, v93
	v_cvt_pk_bf16_f32 v223, v94, v95
	v_add_f32_e32 v187, v80, v187
	v_add_f32_e32 v192, v81, v192
	v_add_f32_e32 v193, v82, v193
	v_add_f32_e32 v194, v83, v194
	s_waitcnt lgkmcnt(3)
	v_mfma_f32_32x32x16_bf16 v[48:63], v[196:199], v[220:223], v[48:63]
	v_add_f32_e32 v187, v108, v187
	v_add_f32_e32 v192, v109, v192
	v_add_f32_e32 v193, v110, v193
	v_add_f32_e32 v194, v111, v194
	v_add_f32_e32 v187, v84, v187
	v_add_f32_e32 v192, v85, v192
	ds_read_b128 v[80:83], v188 offset:16384
	ds_read_b64_tr_b16 v[224:225], v174 offset:16384
	ds_read_b64_tr_b16 v[226:227], v175 offset:18432
	v_mfma_f32_32x32x16_bf16 v[32:47], v[200:203], v[220:223], v[32:47]
	v_add_f32_e32 v193, v86, v193
	v_add_f32_e32 v194, v87, v194
	v_add_f32_e32 v187, v88, v187
	v_add_f32_e32 v192, v89, v192
	v_add_f32_e32 v193, v90, v193
	v_add_f32_e32 v194, v91, v194
	ds_read_b64_tr_b16 v[228:229], v176 offset:16384
	ds_read_b64_tr_b16 v[230:231], v177 offset:18432
	v_mfma_f32_32x32x16_bf16 v[16:31], v[204:207], v[220:223], v[16:31]
	v_add_f32_e32 v187, v92, v187
	v_add_f32_e32 v192, v93, v192
	v_add_f32_e32 v193, v94, v193
	v_add_f32_e32 v194, v95, v194
	ds_read_b64_tr_b16 v[232:233], v178 offset:16384
	ds_read_b64_tr_b16 v[234:235], v179 offset:18432
	v_mfma_f32_32x32x16_bf16 v[0:15], v[246:249], v[220:223], v[0:15]
	ds_read_b64_tr_b16 v[236:237], v183 offset:16384
	ds_read_b64_tr_b16 v[238:239], v184 offset:18432
	s_add_i32 s10, s68, -3
	s_min_u32 s10, s10, s24
	s_lshl_b32 s10, s10, 15
	s_add_u32 s22, s20, s10
	s_addc_u32 s23, s21, 0
	s_waitcnt vmcnt(8)
	s_barrier
; __device__ __forceinline__ void glds16x4(const void* k0, const void* k1, const void* v0, const void* v1, unsigned voff, unsigned lk0, unsigned lk1, unsigned lv0, unsigned lv1) { unsigned keep;
;     asm volatile("s_mov_b32 %0, m0\n\t"
;                  "s_mov_b32 m0, %6\n\ts_nop 0\n\tglobal_load_lds_dwordx4 %1, %2\n\t"
;                  "s_mov_b32 m0, %7\n\ts_nop 0\n\tglobal_load_lds_dwordx4 %1, %3\n\t"
;                  "s_mov_b32 m0, %8\n\ts_nop 0\n\tglobal_load_lds_dwordx4 %1, %4\n\t"
;                  "s_mov_b32 m0, %9\n\ts_nop 0\n\tglobal_load_lds_dwordx4 %1, %5\n\t"
;                  "s_mov_b32 m0, %0"
;                  : "=&s"(keep) : "v"(voff), "s"(k0), "s"(k1), "s"(v0), "s"(v1), "s"(lk0), "s"(lk1), "s"(lv0), "s"(lv1) : "memory"); }
	s_mov_b32 m0, s43
	v_mfma_f32_32x32x16_bf16 v[96:111], v[132:135], v[116:119], v[64:79]
	global_load_lds_dwordx4 v163, s[22:23]
	s_add_i32 m0, s43, 0xfffff000
	s_nop 0
	global_load_lds_dwordx4 v250, s[22:23]
	s_mov_b32 m0, s45
	v_mfma_f32_32x32x16_bf16 v[96:111], v[140:143], v[120:123], v[96:111]
	global_load_lds_dwordx4 v254, s[22:23]
	s_add_i32 m0, s45, 0xfffff000
	s_nop 0
	global_load_lds_dwordx4 v251, s[22:23]
	s_mov_b32 m0, s44
	s_waitcnt lgkmcnt(10)
	v_mfma_f32_32x32x16_bf16 v[96:111], v[148:151], v[124:127], v[96:111]
	global_load_lds_dwordx4 v255, s[22:23]
	ds_read_b64_tr_b16 v[132:133], v176 offset:20480
	ds_read_b64_tr_b16 v[134:135], v177 offset:22528
	s_mov_b32 m0, s48
	s_waitcnt lgkmcnt(10)
	v_mfma_f32_32x32x16_bf16 v[96:111], v[80:83], v[112:115], v[96:111]
	global_load_lds_dwordx4 v253, s[22:23]
	ds_read_b64_tr_b16 v[140:141], v183 offset:20480
	ds_read_b64_tr_b16 v[142:143], v184 offset:22528
	s_add_i32 m0, s44, 0xfffff000
	v_mfma_f32_32x32x16_bf16 v[80:95], v[128:131], v[112:115], v[64:79]
	global_load_lds_dwordx4 v252, s[22:23]
	ds_read_b64_tr_b16 v[128:129], v174 offset:20480
	ds_read_b64_tr_b16 v[130:131], v175 offset:22528
	s_add_i32 m0, s48, 0xfffff000
	v_mfma_f32_32x32x16_bf16 v[80:95], v[136:139], v[116:119], v[80:95]
	global_load_lds_dwordx4 v195, s[22:23]
	s_nop 1
	v_mfma_f32_32x32x16_bf16 v[80:95], v[144:147], v[120:123], v[80:95]
	v_exp_f32_e32 v96, v96
	v_exp_f32_e32 v97, v97
	v_exp_f32_e32 v98, v98
	v_mfma_f32_32x32x16_bf16 v[80:95], v[152:155], v[124:127], v[80:95]
	v_exp_f32_e32 v99, v99
	v_exp_f32_e32 v100, v100
	v_exp_f32_e32 v101, v101
	v_exp_f32_e32 v102, v102
	v_exp_f32_e32 v103, v103
	v_cvt_pk_bf16_f32 v208, v96, v97
	v_cvt_pk_bf16_f32 v209, v98, v99
	v_cvt_pk_bf16_f32 v210, v100, v101
	v_cvt_pk_bf16_f32 v211, v102, v103
	v_exp_f32_e32 v104, v104
	v_exp_f32_e32 v105, v105
	s_waitcnt lgkmcnt(6)
	v_mfma_f32_32x32x16_bf16 v[48:63], v[224:227], v[208:211], v[48:63]
	v_exp_f32_e32 v106, v106
	v_exp_f32_e32 v107, v107
	v_exp_f32_e32 v108, v108
	ds_read_b64_tr_b16 v[136:137], v178 offset:20480
	ds_read_b64_tr_b16 v[138:139], v179 offset:22528
	v_mfma_f32_32x32x16_bf16 v[32:47], v[228:231], v[208:211], v[32:47]
	v_exp_f32_e32 v109, v109
	v_exp_f32_e32 v110, v110
	v_exp_f32_e32 v111, v111
	ds_read_b64_tr_b16 v[144:145], v174 offset:24576
	ds_read_b64_tr_b16 v[146:147], v175 offset:26624
	v_mfma_f32_32x32x16_bf16 v[16:31], v[232:235], v[208:211], v[16:31]
	v_cvt_pk_bf16_f32 v212, v104, v105
	v_cvt_pk_bf16_f32 v213, v106, v107
	v_cvt_pk_bf16_f32 v214, v108, v109
	v_cvt_pk_bf16_f32 v215, v110, v111
	v_add_f32_e32 v187, v96, v187
	v_add_f32_e32 v192, v97, v192
	ds_read_b64_tr_b16 v[148:149], v176 offset:24576
	ds_read_b64_tr_b16 v[150:151], v177 offset:26624
	v_mfma_f32_32x32x16_bf16 v[0:15], v[236:239], v[208:211], v[0:15]
	v_add_f32_e32 v193, v98, v193
	v_add_f32_e32 v194, v99, v194
	v_add_f32_e32 v187, v100, v187
	v_add_f32_e32 v192, v101, v192
	v_add_f32_e32 v193, v102, v193
	v_add_f32_e32 v194, v103, v194
	ds_read_b64_tr_b16 v[152:153], v178 offset:24576
	ds_read_b64_tr_b16 v[154:155], v179 offset:26624
	s_waitcnt lgkmcnt(6)
	v_mfma_f32_32x32x16_bf16 v[48:63], v[128:131], v[212:215], v[48:63]
	v_exp_f32_e32 v80, v80
	v_exp_f32_e32 v81, v81
	v_exp_f32_e32 v82, v82
	ds_read_b64_tr_b16 v[240:241], v183 offset:24576
	ds_read_b64_tr_b16 v[242:243], v184 offset:26624
	ds_read_b128 v[128:131], v188 offset:40960
	v_mfma_f32_32x32x16_bf16 v[32:47], v[132:135], v[212:215], v[32:47]
	v_exp_f32_e32 v83, v83
	v_exp_f32_e32 v84, v84
	v_exp_f32_e32 v85, v85
	ds_read_b64_tr_b16 v[196:197], v174 offset:28672
	ds_read_b64_tr_b16 v[198:199], v175 offset:30720
	ds_read_b128 v[132:135], v189 offset:32768
	v_mfma_f32_32x32x16_bf16 v[16:31], v[136:139], v[212:215], v[16:31]
	v_exp_f32_e32 v86, v86
	v_exp_f32_e32 v87, v87
	v_cvt_pk_bf16_f32 v216, v80, v81
	v_cvt_pk_bf16_f32 v217, v82, v83
	ds_read_b64_tr_b16 v[200:201], v176 offset:28672
	ds_read_b64_tr_b16 v[202:203], v177 offset:30720
	ds_read_b128 v[136:139], v189 offset:40960
	v_mfma_f32_32x32x16_bf16 v[0:15], v[140:143], v[212:215], v[0:15]
	v_cvt_pk_bf16_f32 v218, v84, v85
	v_cvt_pk_bf16_f32 v219, v86, v87
	v_add_f32_e32 v187, v104, v187
	v_add_f32_e32 v192, v105, v192
	v_add_f32_e32 v193, v106, v193
	v_add_f32_e32 v194, v107, v194
	s_waitcnt lgkmcnt(12)
	ds_read_b64_tr_b16 v[204:205], v178 offset:28672
	ds_read_b64_tr_b16 v[206:207], v179 offset:30720
	ds_read_b128 v[140:143], v190 offset:32768
	s_waitcnt lgkmcnt(10)
	v_mfma_f32_32x32x16_bf16 v[48:63], v[144:147], v[216:219], v[48:63]
	v_exp_f32_e32 v88, v88
	v_exp_f32_e32 v89, v89
	v_exp_f32_e32 v90, v90
	ds_read_b64_tr_b16 v[246:247], v183 offset:28672
	ds_read_b64_tr_b16 v[248:249], v184 offset:30720
	ds_read_b128 v[144:147], v190 offset:40960
	v_mfma_f32_32x32x16_bf16 v[32:47], v[148:151], v[216:219], v[32:47]
	v_exp_f32_e32 v91, v91
	v_exp_f32_e32 v92, v92
	v_exp_f32_e32 v93, v93
	ds_read_b128 v[148:151], v191 offset:32768
	v_mfma_f32_32x32x16_bf16 v[16:31], v[152:155], v[216:219], v[16:31]
	v_exp_f32_e32 v94, v94
	v_exp_f32_e32 v95, v95
	v_cvt_pk_bf16_f32 v220, v88, v89
	v_cvt_pk_bf16_f32 v221, v90, v91
	ds_read_b128 v[152:155], v191 offset:40960
	v_mfma_f32_32x32x16_bf16 v[0:15], v[240:243], v[216:219], v[0:15]
	v_cvt_pk_bf16_f32 v222, v92, v93
	v_cvt_pk_bf16_f32 v223, v94, v95
	v_add_f32_e32 v187, v80, v187
	v_add_f32_e32 v192, v81, v192
	v_add_f32_e32 v193, v82, v193
	v_add_f32_e32 v194, v83, v194
	s_waitcnt lgkmcnt(3)
	v_mfma_f32_32x32x16_bf16 v[48:63], v[196:199], v[220:223], v[48:63]
	v_add_f32_e32 v187, v108, v187
	v_add_f32_e32 v192, v109, v192
	v_add_f32_e32 v193, v110, v193
	v_add_f32_e32 v194, v111, v194
	v_add_f32_e32 v187, v84, v187
	v_add_f32_e32 v192, v85, v192
	ds_read_b128 v[80:83], v188 offset:32768
	ds_read_b64_tr_b16 v[224:225], v174 offset:32768
	ds_read_b64_tr_b16 v[226:227], v175 offset:34816
	v_mfma_f32_32x32x16_bf16 v[32:47], v[200:203], v[220:223], v[32:47]
	v_add_f32_e32 v193, v86, v193
	v_add_f32_e32 v194, v87, v194
	v_add_f32_e32 v187, v88, v187
	v_add_f32_e32 v192, v89, v192
	v_add_f32_e32 v193, v90, v193
	v_add_f32_e32 v194, v91, v194
	ds_read_b64_tr_b16 v[228:229], v176 offset:32768
	ds_read_b64_tr_b16 v[230:231], v177 offset:34816
	v_mfma_f32_32x32x16_bf16 v[16:31], v[204:207], v[220:223], v[16:31]
	v_add_f32_e32 v187, v92, v187
	v_add_f32_e32 v192, v93, v192
	v_add_f32_e32 v193, v94, v193
	v_add_f32_e32 v194, v95, v194
	ds_read_b64_tr_b16 v[232:233], v178 offset:32768
	ds_read_b64_tr_b16 v[234:235], v179 offset:34816
	v_mfma_f32_32x32x16_bf16 v[0:15], v[246:249], v[220:223], v[0:15]
	ds_read_b64_tr_b16 v[236:237], v183 offset:32768
	ds_read_b64_tr_b16 v[238:239], v184 offset:34816
	s_add_i32 s10, s68, -2
	s_min_u32 s10, s10, s24
	s_lshl_b32 s10, s10, 15
	s_add_u32 s4, s20, s10
	s_addc_u32 s5, s21, 0
	s_waitcnt vmcnt(8)
	s_barrier
; __device__ __forceinline__ void glds16x4(const void* k0, const void* k1, const void* v0, const void* v1, unsigned voff, unsigned lk0, unsigned lk1, unsigned lv0, unsigned lv1) { unsigned keep;
;     asm volatile("s_mov_b32 %0, m0\n\t"
;                  "s_mov_b32 m0, %6\n\ts_nop 0\n\tglobal_load_lds_dwordx4 %1, %2\n\t"
;                  "s_mov_b32 m0, %7\n\ts_nop 0\n\tglobal_load_lds_dwordx4 %1, %3\n\t"
;                  "s_mov_b32 m0, %8\n\ts_nop 0\n\tglobal_load_lds_dwordx4 %1, %4\n\t"
;                  "s_mov_b32 m0, %9\n\ts_nop 0\n\tglobal_load_lds_dwordx4 %1, %5\n\t"
;                  "s_mov_b32 m0, %0"
;                  : "=&s"(keep) : "v"(voff), "s"(k0), "s"(k1), "s"(v0), "s"(v1), "s"(lk0), "s"(lk1), "s"(lv0), "s"(lv1) : "memory"); }
	s_mov_b32 m0, s46
	v_mfma_f32_32x32x16_bf16 v[96:111], v[132:135], v[116:119], v[64:79]
	global_load_lds_dwordx4 v163, s[4:5]
	s_add_i32 m0, s46, 0xfffff000
	s_nop 0
	global_load_lds_dwordx4 v250, s[4:5]
	s_mov_b32 m0, s47
	v_mfma_f32_32x32x16_bf16 v[96:111], v[140:143], v[120:123], v[96:111]
	global_load_lds_dwordx4 v254, s[4:5]
	s_add_i32 m0, s47, 0xfffff000
	s_nop 0
	global_load_lds_dwordx4 v251, s[4:5]
	s_mov_b32 m0, s51
	s_waitcnt lgkmcnt(10)
	v_mfma_f32_32x32x16_bf16 v[96:111], v[148:151], v[124:127], v[96:111]
	global_load_lds_dwordx4 v255, s[4:5]
	ds_read_b64_tr_b16 v[132:133], v176 offset:36864
	ds_read_b64_tr_b16 v[134:135], v177 offset:38912
	s_mov_b32 m0, s52
	s_waitcnt lgkmcnt(10)
	v_mfma_f32_32x32x16_bf16 v[96:111], v[80:83], v[112:115], v[96:111]
	global_load_lds_dwordx4 v253, s[4:5]
	ds_read_b64_tr_b16 v[140:141], v183 offset:36864
	ds_read_b64_tr_b16 v[142:143], v184 offset:38912
	s_add_i32 m0, s51, 0xfffff000
	v_mfma_f32_32x32x16_bf16 v[80:95], v[128:131], v[112:115], v[64:79]
	global_load_lds_dwordx4 v252, s[4:5]
	ds_read_b64_tr_b16 v[128:129], v174 offset:36864
	ds_read_b64_tr_b16 v[130:131], v175 offset:38912
	s_add_i32 m0, s52, 0xfffff000
	v_mfma_f32_32x32x16_bf16 v[80:95], v[136:139], v[116:119], v[80:95]
	global_load_lds_dwordx4 v195, s[4:5]
	s_nop 1
	v_mfma_f32_32x32x16_bf16 v[80:95], v[144:147], v[120:123], v[80:95]
	v_exp_f32_e32 v96, v96
	v_exp_f32_e32 v97, v97
	v_exp_f32_e32 v98, v98
	v_mfma_f32_32x32x16_bf16 v[80:95], v[152:155], v[124:127], v[80:95]
	v_exp_f32_e32 v99, v99
	v_exp_f32_e32 v100, v100
	v_exp_f32_e32 v101, v101
	v_exp_f32_e32 v102, v102
	v_exp_f32_e32 v103, v103
	v_cvt_pk_bf16_f32 v208, v96, v97
	v_cvt_pk_bf16_f32 v209, v98, v99
	v_cvt_pk_bf16_f32 v210, v100, v101
	v_cvt_pk_bf16_f32 v211, v102, v103
	v_exp_f32_e32 v104, v104
	v_exp_f32_e32 v105, v105
	s_waitcnt lgkmcnt(6)
	v_mfma_f32_32x32x16_bf16 v[48:63], v[224:227], v[208:211], v[48:63]
	v_exp_f32_e32 v106, v106
	v_exp_f32_e32 v107, v107
	v_exp_f32_e32 v108, v108
	ds_read_b64_tr_b16 v[136:137], v178 offset:36864
	ds_read_b64_tr_b16 v[138:139], v179 offset:38912
	v_mfma_f32_32x32x16_bf16 v[32:47], v[228:231], v[208:211], v[32:47]
	v_exp_f32_e32 v109, v109
	v_exp_f32_e32 v110, v110
	v_exp_f32_e32 v111, v111
	ds_read_b64_tr_b16 v[144:145], v174 offset:40960
	ds_read_b64_tr_b16 v[146:147], v175 offset:43008
	v_mfma_f32_32x32x16_bf16 v[16:31], v[232:235], v[208:211], v[16:31]
	v_cvt_pk_bf16_f32 v212, v104, v105
	v_cvt_pk_bf16_f32 v213, v106, v107
	v_cvt_pk_bf16_f32 v214, v108, v109
	v_cvt_pk_bf16_f32 v215, v110, v111
	v_add_f32_e32 v187, v96, v187
	v_add_f32_e32 v192, v97, v192
	ds_read_b64_tr_b16 v[148:149], v176 offset:40960
	ds_read_b64_tr_b16 v[150:151], v177 offset:43008
	v_mfma_f32_32x32x16_bf16 v[0:15], v[236:239], v[208:211], v[0:15]
	v_add_f32_e32 v193, v98, v193
	v_add_f32_e32 v194, v99, v194
	v_add_f32_e32 v187, v100, v187
	v_add_f32_e32 v192, v101, v192
	v_add_f32_e32 v193, v102, v193
	v_add_f32_e32 v194, v103, v194
	ds_read_b64_tr_b16 v[152:153], v178 offset:40960
	ds_read_b64_tr_b16 v[154:155], v179 offset:43008
	s_waitcnt lgkmcnt(6)
	v_mfma_f32_32x32x16_bf16 v[48:63], v[128:131], v[212:215], v[48:63]
	v_exp_f32_e32 v80, v80
	v_exp_f32_e32 v81, v81
	v_exp_f32_e32 v82, v82
	ds_read_b64_tr_b16 v[240:241], v183 offset:40960
	ds_read_b64_tr_b16 v[242:243], v184 offset:43008
	ds_read_b128 v[128:131], v188 offset:57344
	v_mfma_f32_32x32x16_bf16 v[32:47], v[132:135], v[212:215], v[32:47]
	v_exp_f32_e32 v83, v83
	v_exp_f32_e32 v84, v84
	v_exp_f32_e32 v85, v85
	ds_read_b64_tr_b16 v[196:197], v174 offset:45056
	ds_read_b64_tr_b16 v[198:199], v175 offset:47104
	ds_read_b128 v[132:135], v189 offset:49152
	v_mfma_f32_32x32x16_bf16 v[16:31], v[136:139], v[212:215], v[16:31]
	v_exp_f32_e32 v86, v86
	v_exp_f32_e32 v87, v87
	v_cvt_pk_bf16_f32 v216, v80, v81
	v_cvt_pk_bf16_f32 v217, v82, v83
	ds_read_b64_tr_b16 v[200:201], v176 offset:45056
	ds_read_b64_tr_b16 v[202:203], v177 offset:47104
	ds_read_b128 v[136:139], v189 offset:57344
	v_mfma_f32_32x32x16_bf16 v[0:15], v[140:143], v[212:215], v[0:15]
	v_cvt_pk_bf16_f32 v218, v84, v85
	v_cvt_pk_bf16_f32 v219, v86, v87
	v_add_f32_e32 v187, v104, v187
	v_add_f32_e32 v192, v105, v192
	v_add_f32_e32 v193, v106, v193
	v_add_f32_e32 v194, v107, v194
	s_waitcnt lgkmcnt(12)
	ds_read_b64_tr_b16 v[204:205], v178 offset:45056
	ds_read_b64_tr_b16 v[206:207], v179 offset:47104
	ds_read_b128 v[140:143], v190 offset:49152
	s_waitcnt lgkmcnt(10)
	v_mfma_f32_32x32x16_bf16 v[48:63], v[144:147], v[216:219], v[48:63]
	v_exp_f32_e32 v88, v88
	v_exp_f32_e32 v89, v89
	v_exp_f32_e32 v90, v90
	ds_read_b64_tr_b16 v[246:247], v183 offset:45056
	ds_read_b64_tr_b16 v[248:249], v184 offset:47104
	ds_read_b128 v[144:147], v190 offset:57344
	v_mfma_f32_32x32x16_bf16 v[32:47], v[148:151], v[216:219], v[32:47]
	v_exp_f32_e32 v91, v91
	v_exp_f32_e32 v92, v92
	v_exp_f32_e32 v93, v93
	ds_read_b128 v[148:151], v191 offset:49152
	v_mfma_f32_32x32x16_bf16 v[16:31], v[152:155], v[216:219], v[16:31]
	v_exp_f32_e32 v94, v94
	v_exp_f32_e32 v95, v95
	v_cvt_pk_bf16_f32 v220, v88, v89
	v_cvt_pk_bf16_f32 v221, v90, v91
	ds_read_b128 v[152:155], v191 offset:57344
	v_mfma_f32_32x32x16_bf16 v[0:15], v[240:243], v[216:219], v[0:15]
	v_cvt_pk_bf16_f32 v222, v92, v93
	v_cvt_pk_bf16_f32 v223, v94, v95
	v_add_f32_e32 v187, v80, v187
	v_add_f32_e32 v192, v81, v192
	v_add_f32_e32 v193, v82, v193
	v_add_f32_e32 v194, v83, v194
	s_waitcnt lgkmcnt(3)
	v_mfma_f32_32x32x16_bf16 v[48:63], v[196:199], v[220:223], v[48:63]
	v_add_f32_e32 v187, v108, v187
	v_add_f32_e32 v192, v109, v192
	v_add_f32_e32 v193, v110, v193
	v_add_f32_e32 v194, v111, v194
	v_add_f32_e32 v187, v84, v187
	v_add_f32_e32 v192, v85, v192
	ds_read_b128 v[80:83], v188 offset:49152
	ds_read_b64_tr_b16 v[224:225], v174 offset:49152
	ds_read_b64_tr_b16 v[226:227], v175 offset:51200
	v_mfma_f32_32x32x16_bf16 v[32:47], v[200:203], v[220:223], v[32:47]
	v_add_f32_e32 v193, v86, v193
	v_add_f32_e32 v194, v87, v194
	v_add_f32_e32 v187, v88, v187
	v_add_f32_e32 v192, v89, v192
	v_add_f32_e32 v193, v90, v193
	v_add_f32_e32 v194, v91, v194
	ds_read_b64_tr_b16 v[228:229], v176 offset:49152
	ds_read_b64_tr_b16 v[230:231], v177 offset:51200
	v_mfma_f32_32x32x16_bf16 v[16:31], v[204:207], v[220:223], v[16:31]
	v_add_f32_e32 v187, v92, v187
	v_add_f32_e32 v192, v93, v192
	v_add_f32_e32 v193, v94, v193
	v_add_f32_e32 v194, v95, v194
	ds_read_b64_tr_b16 v[232:233], v178 offset:49152
	ds_read_b64_tr_b16 v[234:235], v179 offset:51200
	v_mfma_f32_32x32x16_bf16 v[0:15], v[246:249], v[220:223], v[0:15]
	ds_read_b64_tr_b16 v[236:237], v183 offset:49152
	ds_read_b64_tr_b16 v[238:239], v184 offset:51200
	s_add_i32 s10, s68, -1
	s_min_u32 s10, s10, s24
	s_lshl_b32 s10, s10, 15
	s_add_u32 s22, s20, s10
	s_addc_u32 s23, s21, 0
	s_waitcnt vmcnt(8)
	s_barrier
; __device__ __forceinline__ void glds16x4(const void* k0, const void* k1, const void* v0, const void* v1, unsigned voff, unsigned lk0, unsigned lk1, unsigned lv0, unsigned lv1) { unsigned keep;
;     asm volatile("s_mov_b32 %0, m0\n\t"
;                  "s_mov_b32 m0, %6\n\ts_nop 0\n\tglobal_load_lds_dwordx4 %1, %2\n\t"
;                  "s_mov_b32 m0, %7\n\ts_nop 0\n\tglobal_load_lds_dwordx4 %1, %3\n\t"
;                  "s_mov_b32 m0, %8\n\ts_nop 0\n\tglobal_load_lds_dwordx4 %1, %4\n\t"
;                  "s_mov_b32 m0, %9\n\ts_nop 0\n\tglobal_load_lds_dwordx4 %1, %5\n\t"
;                  "s_mov_b32 m0, %0"
;                  : "=&s"(keep) : "v"(voff), "s"(k0), "s"(k1), "s"(v0), "s"(v1), "s"(lk0), "s"(lk1), "s"(lv0), "s"(lv1) : "memory"); }
; __device__ __forceinline__ void attn_unit(LAS unsigned char* L, bf16_t* QKV, size_t rowbase, int S, int h, int qb, float lam, const float* subln, unsigned* kmax) {
;     ...
;     for (int t = 0; t < NT; t += 4) { TILE(t, 0); TILE(t + 1, 1); TILE(t + 2, 2); TILE(t + 3, 3); }
	s_mov_b32 m0, s49
	v_mfma_f32_32x32x16_bf16 v[96:111], v[132:135], v[116:119], v[64:79]
	global_load_lds_dwordx4 v163, s[22:23]
	s_add_i32 m0, s49, 0xfffff000
	s_nop 0
	global_load_lds_dwordx4 v250, s[22:23]
	s_mov_b32 m0, s50
	v_mfma_f32_32x32x16_bf16 v[96:111], v[140:143], v[120:123], v[96:111]
	global_load_lds_dwordx4 v254, s[22:23]
	s_add_i32 m0, s50, 0xfffff000
	s_nop 0
	global_load_lds_dwordx4 v251, s[22:23]
	s_mov_b32 m0, s59
	s_waitcnt lgkmcnt(10)
	v_mfma_f32_32x32x16_bf16 v[96:111], v[148:151], v[124:127], v[96:111]
	global_load_lds_dwordx4 v255, s[22:23]
	ds_read_b64_tr_b16 v[132:133], v176 offset:53248
	ds_read_b64_tr_b16 v[134:135], v177 offset:55296
	s_mov_b32 m0, s61
	s_waitcnt lgkmcnt(10)
	v_mfma_f32_32x32x16_bf16 v[96:111], v[80:83], v[112:115], v[96:111]
	global_load_lds_dwordx4 v253, s[22:23]
	ds_read_b64_tr_b16 v[140:141], v183 offset:53248
	ds_read_b64_tr_b16 v[142:143], v184 offset:55296
	s_add_i32 m0, s59, 0xfffff000
	v_mfma_f32_32x32x16_bf16 v[80:95], v[128:131], v[112:115], v[64:79]
	global_load_lds_dwordx4 v252, s[22:23]
	ds_read_b64_tr_b16 v[128:129], v174 offset:53248
	ds_read_b64_tr_b16 v[130:131], v175 offset:55296
	s_add_i32 m0, s61, 0xfffff000
	v_mfma_f32_32x32x16_bf16 v[80:95], v[136:139], v[116:119], v[80:95]
	global_load_lds_dwordx4 v195, s[22:23]
	s_nop 1
	v_mfma_f32_32x32x16_bf16 v[80:95], v[144:147], v[120:123], v[80:95]
	v_exp_f32_e32 v96, v96
	v_exp_f32_e32 v97, v97
	v_exp_f32_e32 v98, v98
	v_mfma_f32_32x32x16_bf16 v[80:95], v[152:155], v[124:127], v[80:95]
	v_exp_f32_e32 v99, v99
	v_exp_f32_e32 v100, v100
	v_exp_f32_e32 v101, v101
	v_exp_f32_e32 v102, v102
	v_exp_f32_e32 v103, v103
	v_cvt_pk_bf16_f32 v208, v96, v97
	v_cvt_pk_bf16_f32 v209, v98, v99
	v_cvt_pk_bf16_f32 v210, v100, v101
	v_cvt_pk_bf16_f32 v211, v102, v103
	v_exp_f32_e32 v104, v104
	v_exp_f32_e32 v105, v105
	s_waitcnt lgkmcnt(6)
	v_mfma_f32_32x32x16_bf16 v[48:63], v[224:227], v[208:211], v[48:63]
	v_exp_f32_e32 v106, v106
	v_exp_f32_e32 v107, v107
	v_exp_f32_e32 v108, v108
	ds_read_b64_tr_b16 v[136:137], v178 offset:53248
	ds_read_b64_tr_b16 v[138:139], v179 offset:55296
	v_mfma_f32_32x32x16_bf16 v[32:47], v[228:231], v[208:211], v[32:47]
	v_exp_f32_e32 v109, v109
	v_exp_f32_e32 v110, v110
	v_exp_f32_e32 v111, v111
	ds_read_b64_tr_b16 v[144:145], v174 offset:57344
	ds_read_b64_tr_b16 v[146:147], v175 offset:59392
	v_mfma_f32_32x32x16_bf16 v[16:31], v[232:235], v[208:211], v[16:31]
	v_cvt_pk_bf16_f32 v212, v104, v105
	v_cvt_pk_bf16_f32 v213, v106, v107
	v_cvt_pk_bf16_f32 v214, v108, v109
	v_cvt_pk_bf16_f32 v215, v110, v111
	v_add_f32_e32 v187, v96, v187
	v_add_f32_e32 v192, v97, v192
	ds_read_b64_tr_b16 v[148:149], v176 offset:57344
	ds_read_b64_tr_b16 v[150:151], v177 offset:59392
	v_mfma_f32_32x32x16_bf16 v[0:15], v[236:239], v[208:211], v[0:15]
	v_add_f32_e32 v193, v98, v193
	v_add_f32_e32 v194, v99, v194
	v_add_f32_e32 v187, v100, v187
	v_add_f32_e32 v192, v101, v192
	v_add_f32_e32 v193, v102, v193
	v_add_f32_e32 v194, v103, v194
	ds_read_b64_tr_b16 v[152:153], v178 offset:57344
	ds_read_b64_tr_b16 v[154:155], v179 offset:59392
	s_waitcnt lgkmcnt(6)
	v_mfma_f32_32x32x16_bf16 v[48:63], v[128:131], v[212:215], v[48:63]
	v_exp_f32_e32 v80, v80
	v_exp_f32_e32 v81, v81
	v_exp_f32_e32 v82, v82
	ds_read_b64_tr_b16 v[240:241], v183 offset:57344
	ds_read_b64_tr_b16 v[242:243], v184 offset:59392
	ds_read_b128 v[128:131], v188 offset:8192
	v_mfma_f32_32x32x16_bf16 v[32:47], v[132:135], v[212:215], v[32:47]
	v_exp_f32_e32 v83, v83
	v_exp_f32_e32 v84, v84
	v_exp_f32_e32 v85, v85
	ds_read_b64_tr_b16 v[196:197], v174 offset:61440
	ds_read_b64_tr_b16 v[198:199], v175 offset:63488
	ds_read_b128 v[132:135], v189
	v_mfma_f32_32x32x16_bf16 v[16:31], v[136:139], v[212:215], v[16:31]
	v_exp_f32_e32 v86, v86
	v_exp_f32_e32 v87, v87
	v_cvt_pk_bf16_f32 v216, v80, v81
	v_cvt_pk_bf16_f32 v217, v82, v83
	ds_read_b64_tr_b16 v[200:201], v176 offset:61440
	ds_read_b64_tr_b16 v[202:203], v177 offset:63488
	ds_read_b128 v[136:139], v189 offset:8192
	v_mfma_f32_32x32x16_bf16 v[0:15], v[140:143], v[212:215], v[0:15]
	v_cvt_pk_bf16_f32 v218, v84, v85
	v_cvt_pk_bf16_f32 v219, v86, v87
	v_add_f32_e32 v187, v104, v187
	v_add_f32_e32 v192, v105, v192
	v_add_f32_e32 v193, v106, v193
	v_add_f32_e32 v194, v107, v194
	s_waitcnt lgkmcnt(12)
	ds_read_b64_tr_b16 v[204:205], v178 offset:61440
	ds_read_b64_tr_b16 v[206:207], v179 offset:63488
	ds_read_b128 v[140:143], v190
	s_waitcnt lgkmcnt(10)
	v_mfma_f32_32x32x16_bf16 v[48:63], v[144:147], v[216:219], v[48:63]
	v_exp_f32_e32 v88, v88
	v_exp_f32_e32 v89, v89
	v_exp_f32_e32 v90, v90
	ds_read_b64_tr_b16 v[246:247], v183 offset:61440
	ds_read_b64_tr_b16 v[248:249], v184 offset:63488
	ds_read_b128 v[144:147], v190 offset:8192
	v_mfma_f32_32x32x16_bf16 v[32:47], v[148:151], v[216:219], v[32:47]
	v_exp_f32_e32 v91, v91
	v_exp_f32_e32 v92, v92
	v_exp_f32_e32 v93, v93
	ds_read_b128 v[148:151], v191
	v_mfma_f32_32x32x16_bf16 v[16:31], v[152:155], v[216:219], v[16:31]
	v_exp_f32_e32 v94, v94
	v_exp_f32_e32 v95, v95
	v_cvt_pk_bf16_f32 v220, v88, v89
	v_cvt_pk_bf16_f32 v221, v90, v91
	ds_read_b128 v[152:155], v191 offset:8192
	v_mfma_f32_32x32x16_bf16 v[0:15], v[240:243], v[216:219], v[0:15]
	v_cvt_pk_bf16_f32 v222, v92, v93
	v_cvt_pk_bf16_f32 v223, v94, v95
	v_add_f32_e32 v187, v80, v187
	v_add_f32_e32 v192, v81, v192
	v_add_f32_e32 v193, v82, v193
	v_add_f32_e32 v194, v83, v194
	s_waitcnt lgkmcnt(3)
	v_mfma_f32_32x32x16_bf16 v[48:63], v[196:199], v[220:223], v[48:63]
	v_add_f32_e32 v187, v108, v187
	v_add_f32_e32 v192, v109, v192
	v_add_f32_e32 v193, v110, v193
	v_add_f32_e32 v194, v111, v194
	v_add_f32_e32 v187, v84, v187
	v_add_f32_e32 v192, v85, v192
	ds_read_b128 v[80:83], v188
	ds_read_b64_tr_b16 v[224:225], v174
	ds_read_b64_tr_b16 v[226:227], v175 offset:2048
	v_mfma_f32_32x32x16_bf16 v[32:47], v[200:203], v[220:223], v[32:47]
	v_add_f32_e32 v193, v86, v193
	v_add_f32_e32 v194, v87, v194
	v_add_f32_e32 v187, v88, v187
	v_add_f32_e32 v192, v89, v192
	v_add_f32_e32 v193, v90, v193
	v_add_f32_e32 v194, v91, v194
	ds_read_b64_tr_b16 v[228:229], v176
	ds_read_b64_tr_b16 v[230:231], v177 offset:2048
	v_mfma_f32_32x32x16_bf16 v[16:31], v[204:207], v[220:223], v[16:31]
	v_add_f32_e32 v187, v92, v187
	v_add_f32_e32 v192, v93, v192
	v_add_f32_e32 v193, v94, v193
	v_add_f32_e32 v194, v95, v194
	ds_read_b64_tr_b16 v[232:233], v178
	ds_read_b64_tr_b16 v[234:235], v179 offset:2048
	v_mfma_f32_32x32x16_bf16 v[0:15], v[246:249], v[220:223], v[0:15]
	ds_read_b64_tr_b16 v[236:237], v183
	ds_read_b64_tr_b16 v[238:239], v184 offset:2048
	s_min_u32 s10, s68, s24
	s_lshl_b32 s10, s10, 15
	s_add_u32 s4, s20, s10
	s_addc_u32 s5, s21, 0
	s_waitcnt vmcnt(8)
	s_add_i32 s68, s68, 4
	s_cmp_ge_u32 s69, s42
	s_barrier
	s_cbranch_scc0 .LG_loop
